# speedup vs baseline: 1.0082x; 1.0024x over previous
.LBB0_9:
	s_sleep 6
	global_load_dword v3, v1, s[6:7] sc1
	s_waitcnt vmcnt(0)
	v_cmp_gt_u32_e32 vcc, s3, v3
	s_cbranch_vccnz .LBB0_9
	buffer_inv sc1
	s_waitcnt vmcnt(0)

.LBB0_88:
	s_sleep 6
	global_load_dword v3, v2, s[6:7] sc1
	s_waitcnt vmcnt(0)
	v_cmp_gt_u32_e32 vcc, s3, v3
	s_cbranch_vccnz .LBB0_88
	buffer_inv sc1
	s_waitcnt vmcnt(0)

.LBB0_132:
	s_sleep 6
	global_load_dword v3, v2, s[4:5] sc1
	s_waitcnt vmcnt(0)
	v_cmp_gt_u32_e32 vcc, s3, v3
	s_cbranch_vccnz .LBB0_132
	buffer_inv sc1
	s_waitcnt vmcnt(0)

.LBB0_506:
	s_sleep 6
	global_load_dword v3, v1, s[4:5] sc1
	s_waitcnt vmcnt(0)
	v_cmp_gt_u32_e32 vcc, s3, v3
	s_cbranch_vccnz .LBB0_506
	buffer_inv sc1
	s_waitcnt vmcnt(0)

.LBB0_566:
	s_sleep 6
	global_load_dword v2, v1, s[6:7] sc1
	s_waitcnt vmcnt(0)
	v_cmp_gt_u32_e32 vcc, s3, v2
	s_cbranch_vccnz .LBB0_566
	buffer_inv sc1
	s_waitcnt vmcnt(0)

.LBB0_966:
	s_sleep 6
	global_load_dword v2, v1, s[4:5] sc1
	s_waitcnt vmcnt(0)
	v_cmp_gt_u32_e32 vcc, s3, v2
	s_cbranch_vccnz .LBB0_966
	buffer_inv sc1
	s_waitcnt vmcnt(0)

.LBB0_1108:
	s_sleep 6
	global_load_dword v2, v1, s[2:3] sc1
	s_waitcnt vmcnt(0)
	v_cmp_gt_u32_e32 vcc, s33, v2
	s_cbranch_vccnz .LBB0_1108
	buffer_inv sc1
	s_waitcnt vmcnt(0)
